# FFN gate-up GEMM epilogue: v_permlane16_swap pairs the two 8B stores of a row into one 16B store (half the store instructions)
# speedup vs baseline: 1.0206x; 1.0140x over previous
; #define GAS __attribute__((address_space(1)))
;     __device__ __forceinline__ void operator()(const f32x4 (&acc)[2][2][4][2], const pg8::Unit& u, int wr, int wc, int fr, int fq) const {
;     ...
;                 for (int m = 0; m < 4; ++m) { const int row = u.pm * 256 + ai * 128 + wr * 64 + m * 16 + fr; pq[ai][m] = *(const GAS f32x4*)(a.ssp + (size_t)row * 16 + 4 * fq); }
; #pragma unroll
;             for (int ai = 0; ai < 2; ++ai)
; #pragma unroll
;                 for (int m = 0; m < 4; ++m) { float sp = (pq[ai][m][0] + pq[ai][m][1]) + (pq[ai][m][2] + pq[ai][m][3]); sp += __shfl_xor(sp, 16); sp += __shfl_xor(sp, 32); rs[ai][m] = rsqrtf(sp * (1.0f / 1024.0f) + EPS); }
.LBB0_314:
	v_bfe_u32 v248, v200, 4, 1
	v_mul_u32_u24_e32 v248, 0x78, v248
	v_mov_b32_e32 v249, 0
	v_readlane_b32 s0, v245, 2
	v_lshl_add_u32 v188, s12, 8, v159
	v_lshlrev_b32_e32 v160, 2, v158
	v_mov_b32_e32 v128, s0
	ds_read_b128 v[128:131], v128
	v_ashrrev_i32_e32 v189, 31, v188
	v_lshlrev_b64 v[132:133], 6, v[188:189]
	v_or_b32_e32 v184, 16, v188
	v_ashrrev_i32_e32 v185, 31, v184
	s_waitcnt lgkmcnt(0)
	v_lshl_add_u64 v[130:131], v[130:131], 0, v[160:161]
	v_lshl_add_u64 v[132:133], v[130:131], 0, v[132:133]
	global_load_dwordx4 v[208:211], v[132:133], off
	v_lshlrev_b64 v[132:133], 6, v[184:185]
	v_lshl_add_u64 v[132:133], v[130:131], 0, v[132:133]
	global_load_dwordx4 v[214:217], v[132:133], off
	v_or_b32_e32 v182, 32, v188
	v_ashrrev_i32_e32 v183, 31, v182
	v_lshlrev_b64 v[132:133], 6, v[182:183]
	v_or_b32_e32 v180, 48, v188
	v_lshl_add_u64 v[132:133], v[130:131], 0, v[132:133]
	v_ashrrev_i32_e32 v181, 31, v180
	global_load_dwordx4 v[150:153], v[132:133], off
	v_lshlrev_b64 v[132:133], 6, v[180:181]
	v_lshl_add_u64 v[132:133], v[130:131], 0, v[132:133]
	global_load_dwordx4 v[146:149], v[132:133], off
	v_add_u32_e32 v178, 0x80, v188
	v_ashrrev_i32_e32 v179, 31, v178
	v_lshlrev_b64 v[132:133], 6, v[178:179]
	v_add_u32_e32 v176, 0x90, v188
	v_lshl_add_u64 v[132:133], v[130:131], 0, v[132:133]
	v_ashrrev_i32_e32 v177, 31, v176
	global_load_dwordx4 v[142:145], v[132:133], off
	v_lshlrev_b64 v[132:133], 6, v[176:177]
	v_lshl_add_u64 v[132:133], v[130:131], 0, v[132:133]
	global_load_dwordx4 v[138:141], v[132:133], off
	v_add_u32_e32 v174, 0xa0, v188
	v_ashrrev_i32_e32 v175, 31, v174
	v_lshlrev_b64 v[132:133], 6, v[174:175]
	v_add_u32_e32 v172, 0xb0, v188
	v_lshl_add_u64 v[132:133], v[130:131], 0, v[132:133]
	v_ashrrev_i32_e32 v173, 31, v172
	global_load_dwordx4 v[134:137], v[132:133], off
	v_lshlrev_b64 v[132:133], 6, v[172:173]
	v_lshl_add_u64 v[130:131], v[130:131], 0, v[132:133]
	global_load_dwordx4 v[130:133], v[130:131], off
	v_and_b32_e32 v173, 64, v200
	v_xor_b32_e32 v160, 16, v200
	v_add_u32_e32 v175, 64, v173
	v_cmp_lt_i32_e32 vcc, v160, v175
	s_mov_b32 s0, 0x358637bd
	s_mov_b32 s12, 0x3a800000
	v_cndmask_b32_e32 v160, v200, v160, vcc
	v_lshlrev_b32_e32 v173, 2, v160
	v_xor_b32_e32 v160, 32, v200
	v_cmp_lt_i32_e32 vcc, v160, v175
	s_movk_i32 s18, 0x1600
	v_readlane_b32 s22, v245, 51
	v_cndmask_b32_e32 v160, v200, v160, vcc
	v_lshlrev_b32_e32 v160, 2, v160
	s_mov_b32 s80, 0x3a800000
	v_readlane_b32 s23, v245, 52
	s_waitcnt vmcnt(0)
	v_mov_b32_e32 v192, v209
	v_mov_b32_e32 v193, v210
	v_mov_b32_e32 v209, v211
	v_pk_add_f32 v[192:193], v[192:193], v[208:209]
	v_mov_b32_e32 v208, v215
	v_mov_b32_e32 v209, v216
	v_mov_b32_e32 v215, v217
	v_pk_add_f32 v[208:209], v[208:209], v[214:215]
	v_mov_b32_e32 v211, v192
	v_mov_b32_e32 v210, v208
	v_mov_b32_e32 v192, v209
	v_pk_add_f32 v[192:193], v[210:211], v[192:193]
	ds_bpermute_b32 v209, v173, v193
	ds_bpermute_b32 v208, v173, v192
	s_waitcnt lgkmcnt(0)
	v_pk_add_f32 v[192:193], v[192:193], v[208:209]
	ds_bpermute_b32 v209, v160, v193
	ds_bpermute_b32 v208, v160, v192
	s_waitcnt lgkmcnt(0)
	v_pk_add_f32 v[208:209], v[192:193], v[208:209]
	v_mov_b64_e32 v[192:193], s[0:1]
	v_pk_fma_f32 v[208:209], v[208:209], s[12:13], v[192:193] op_sel_hi:[1,0,0]
	s_nop 0
	v_mul_f32_e32 v175, 0x4b800000, v209
	v_cmp_gt_f32_e64 s[0:1], s3, v209
	v_cmp_gt_f32_e32 vcc, s3, v208
	s_nop 0
	v_cndmask_b32_e64 v175, v209, v175, s[0:1]
	v_rsq_f32_e32 v175, v175
	v_mov_b32_e32 v209, v152
	v_mov_b32_e32 v152, v147
	v_mov_b32_e32 v147, v149
	v_mul_f32_e32 v177, 0x45800000, v175
	v_cndmask_b32_e64 v190, v175, v177, s[0:1]
	v_mul_f32_e32 v175, 0x4b800000, v208
	v_cndmask_b32_e32 v175, v208, v175, vcc
	v_mov_b32_e32 v208, v151
	v_mov_b32_e32 v151, v153
	v_mov_b32_e32 v153, v148
	v_pk_add_f32 v[150:151], v[208:209], v[150:151]
	v_pk_add_f32 v[146:147], v[152:153], v[146:147]
	v_mov_b32_e32 v149, v150
	v_mov_b32_e32 v148, v146
	v_mov_b32_e32 v150, v147
	v_pk_add_f32 v[146:147], v[148:149], v[150:151]
	ds_bpermute_b32 v149, v173, v147
	ds_bpermute_b32 v148, v173, v146
	v_mov_b32_e32 v150, v143
	v_mov_b32_e32 v151, v144
	v_mov_b32_e32 v143, v145
	v_mov_b32_e32 v144, v139
	v_mov_b32_e32 v145, v140
	v_mov_b32_e32 v139, v141
	v_pk_add_f32 v[142:143], v[150:151], v[142:143]
	v_pk_add_f32 v[138:139], v[144:145], v[138:139]
	s_waitcnt lgkmcnt(0)
	v_pk_add_f32 v[146:147], v[146:147], v[148:149]
	v_mov_b32_e32 v140, v138
	v_mov_b32_e32 v141, v142
	v_mov_b32_e32 v142, v139
	ds_bpermute_b32 v149, v160, v147
	ds_bpermute_b32 v148, v160, v146
	v_pk_add_f32 v[138:139], v[140:141], v[142:143]
	ds_bpermute_b32 v141, v173, v139
	ds_bpermute_b32 v140, v173, v138
	v_mov_b32_e32 v142, v135
	v_mov_b32_e32 v143, v136
	v_mov_b32_e32 v135, v137
	v_mov_b32_e32 v136, v131
	v_mov_b32_e32 v137, v132
	v_mov_b32_e32 v131, v133
	s_waitcnt lgkmcnt(2)
	v_pk_add_f32 v[146:147], v[146:147], v[148:149]
	v_pk_add_f32 v[134:135], v[142:143], v[134:135]
	v_pk_add_f32 v[130:131], v[136:137], v[130:131]
	v_pk_fma_f32 v[146:147], v[146:147], s[12:13], v[192:193] op_sel_hi:[1,0,0]
	s_waitcnt lgkmcnt(0)
	v_pk_add_f32 v[138:139], v[138:139], v[140:141]
	v_mov_b32_e32 v132, v130
	v_mov_b32_e32 v133, v134
	v_mov_b32_e32 v134, v131
	v_mul_f32_e32 v148, 0x4b800000, v147
	v_cmp_gt_f32_e64 s[0:1], s3, v147
	ds_bpermute_b32 v141, v160, v139
	ds_bpermute_b32 v140, v160, v138
	v_pk_add_f32 v[130:131], v[132:133], v[134:135]
	v_cndmask_b32_e64 v147, v147, v148, s[0:1]
	ds_bpermute_b32 v133, v173, v131
	ds_bpermute_b32 v132, v173, v130
	v_rsq_f32_e32 v175, v175
	v_rsq_f32_e32 v147, v147
	s_waitcnt lgkmcnt(2)
; #define GAS __attribute__((address_space(1)))
; __device__ __forceinline__ unsigned pk2(float lo, float hi) { const f32x2 v = {lo, hi}; return __builtin_bit_cast(unsigned, __builtin_convertvector(v, hwbf16x2)); }
; __device__ __forceinline__ float silu_f(float x) { return x * fast_rcp(1.0f + __expf(-x)); }
; template <int MODE, bool SMALL>
; __device__ __forceinline__ float epi_apply(const EpiArgs& a, int row, int g32, int fq, f32x4 v0, f32x4 v1, float rstd) {
;     ...
;         v0 *= rstd; v1 *= rstd;
;         float h[4];
; #pragma unroll
;         for (int j = 0; j < 4; ++j) h[j] = silu_f(v0[j]) * v1[j];
;         u32x2 w; w.x = pk2(h[0], h[1]); w.y = pk2(h[2], h[3]);
;         *(GAS u32x2*)(a.out + (size_t)row * DFF + 16 * g32 + 4 * fq) = w;
;     __device__ __forceinline__ void operator()(const f32x4 (&acc)[2][2][4][2], const pg8::Unit& u, int wr, int wc, int fr, int fq) const {
;     ...
;                 for (int m = 0; m < 4; ++m) {
;                     const int row = u.pm * 256 + ai * 128 + wr * 64 + m * 16 + fr;
; #pragma unroll
;                     for (int bj = 0; bj < 2; ++bj) { const int g32 = (u.pn * 256 + bj * 128 + wc * 32) >> 5; (void)epi_apply<MODE, false>(a, row, g32, fq, acc[ai][bj][m][0], acc[ai][bj][m][1], rs[ai][m]); }
	v_pk_add_f32 v[138:139], v[138:139], v[140:141]
	v_pk_mul_f32 v[124:125], v[124:125], v[190:191] op_sel_hi:[1,0]
	v_mul_f32_e32 v177, 0x45800000, v175
	v_mul_f32_e32 v148, 0x45800000, v147
	v_pk_fma_f32 v[138:139], v[138:139], s[12:13], v[192:193] op_sel_hi:[1,0,0]
	s_waitcnt lgkmcnt(0)
	v_pk_add_f32 v[130:131], v[130:131], v[132:133]
	v_cndmask_b32_e32 v186, v175, v177, vcc
	v_cmp_gt_f32_e32 vcc, s3, v146
	v_cndmask_b32_e64 v148, v147, v148, s[0:1]
	v_mul_f32_e32 v147, 0x4b800000, v146
	v_mul_f32_e32 v140, 0x4b800000, v139
	v_cmp_gt_f32_e64 s[0:1], s3, v139
	ds_bpermute_b32 v133, v160, v131
	ds_bpermute_b32 v132, v160, v130
	v_cndmask_b32_e32 v146, v146, v147, vcc
	v_cndmask_b32_e64 v139, v139, v140, s[0:1]
	v_rsq_f32_e32 v146, v146
	v_rsq_f32_e32 v139, v139
	s_waitcnt lgkmcnt(0)
	v_pk_add_f32 v[130:131], v[130:131], v[132:133]
	v_pk_mul_f32 v[126:127], v[126:127], v[190:191] op_sel_hi:[1,0]
	v_mul_f32_e32 v147, 0x45800000, v146
	v_mul_f32_e32 v140, 0x45800000, v139
	v_pk_fma_f32 v[130:131], v[130:131], s[12:13], v[192:193] op_sel_hi:[1,0,0]
	v_cndmask_b32_e32 v146, v146, v147, vcc
	v_cmp_gt_f32_e32 vcc, s3, v138
	v_cndmask_b32_e64 v140, v139, v140, s[0:1]
	v_mul_f32_e32 v139, 0x4b800000, v138
	v_mul_f32_e32 v132, 0x4b800000, v131
	v_cmp_gt_f32_e64 s[0:1], s3, v131
	v_cndmask_b32_e32 v138, v138, v139, vcc
	v_rsq_f32_e32 v138, v138
	v_cndmask_b32_e64 v131, v131, v132, s[0:1]
	v_rsq_f32_e32 v131, v131
	v_pk_mul_f32 v[120:121], v[120:121], v[190:191] op_sel_hi:[1,0]
	v_mul_f32_e32 v139, 0x45800000, v138
	v_cndmask_b32_e32 v138, v138, v139, vcc
	v_mul_f32_e32 v132, 0x45800000, v131
	v_cmp_gt_f32_e32 vcc, s3, v130
	v_cndmask_b32_e64 v132, v131, v132, s[0:1]
	v_mul_f32_e32 v131, 0x4b800000, v130
	v_cndmask_b32_e32 v130, v130, v131, vcc
	v_rsq_f32_e32 v130, v130
	v_lshlrev_b32_e32 v160, 1, v158
	s_lshl_b32 s0, s4, 8
	v_lshl_add_u64 v[128:129], v[128:129], 0, v[160:161]
	v_mul_f32_e32 v131, 0x45800000, v130
	v_cndmask_b32_e32 v130, v130, v131, vcc
	v_mul_f32_e32 v131, 0xbfb8aa3b, v124
	v_exp_f32_e32 v131, v131
	s_or_b32 s4, s0, s60
	v_mad_i64_i32 v[134:135], s[0:1], v188, s18, v[128:129]
	v_add_f32_e32 v131, 1.0, v131
	v_rcp_f32_e32 v136, v131
	v_mul_f32_e32 v131, 0xbfb8aa3b, v125
	v_exp_f32_e32 v131, v131
	s_ashr_i32 s0, s4, 1
	v_pk_mul_f32 v[122:123], v[122:123], v[190:191] op_sel_hi:[1,0]
	s_ashr_i32 s1, s0, 31
	v_add_f32_e32 v131, 1.0, v131
	v_rcp_f32_e32 v137, v131
	s_lshl_b64 s[0:1], s[0:1], 1
	v_pk_mul_f32 v[116:117], v[116:117], v[190:191] op_sel_hi:[1,0]
	v_pk_mul_f32 v[118:119], v[118:119], v[190:191] op_sel_hi:[1,0]
	v_pk_mul_f32 v[124:125], v[124:125], v[136:137]
	v_pk_mul_f32 v[112:113], v[112:113], v[190:191] op_sel_hi:[1,0]
	v_pk_mul_f32 v[120:121], v[120:121], v[124:125]
	v_mul_f32_e32 v124, 0xbfb8aa3b, v126
	v_mul_f32_e32 v125, 0xbfb8aa3b, v127
	v_exp_f32_e32 v124, v124
	v_exp_f32_e32 v125, v125
	v_cvt_pk_bf16_f32 v120, v120, v121
	v_pk_mul_f32 v[114:115], v[114:115], v[190:191] op_sel_hi:[1,0]
	v_add_f32_e32 v124, 1.0, v124
	v_add_f32_e32 v125, 1.0, v125
	v_rcp_f32_e32 v124, v124
	v_rcp_f32_e32 v125, v125
	v_pk_mul_f32 v[108:109], v[108:109], v[186:187] op_sel_hi:[1,0]
	v_pk_mul_f32 v[110:111], v[110:111], v[186:187] op_sel_hi:[1,0]
	v_pk_mul_f32 v[104:105], v[104:105], v[186:187] op_sel_hi:[1,0]
	v_pk_mul_f32 v[124:125], v[126:127], v[124:125]
	v_pk_mul_f32 v[106:107], v[106:107], v[186:187] op_sel_hi:[1,0]
	v_pk_mul_f32 v[122:123], v[122:123], v[124:125]
	v_pk_mul_f32 v[100:101], v[100:101], v[186:187] op_sel_hi:[1,0]
	v_cvt_pk_bf16_f32 v121, v122, v123
	v_lshl_add_u64 v[122:123], v[134:135], 0, s[0:1]
	v_mov_b32_e32 v250, v120
	v_mov_b32_e32 v251, v121
	v_mul_f32_e32 v120, 0xbfb8aa3b, v116
	v_mul_f32_e32 v121, 0xbfb8aa3b, v117
	v_exp_f32_e32 v120, v120
	v_exp_f32_e32 v121, v121
	v_pk_mul_f32 v[102:103], v[102:103], v[186:187] op_sel_hi:[1,0]
	v_pk_mul_f32 v[96:97], v[96:97], v[186:187] op_sel_hi:[1,0]
	v_add_f32_e32 v120, 1.0, v120
	v_add_f32_e32 v121, 1.0, v121
	v_rcp_f32_e32 v120, v120
	v_rcp_f32_e32 v121, v121
	v_pk_mul_f32 v[98:99], v[98:99], v[186:187] op_sel_hi:[1,0]
	v_pk_mul_f32 v[92:93], v[92:93], v[148:149] op_sel_hi:[1,0]
	v_pk_mul_f32 v[94:95], v[94:95], v[148:149] op_sel_hi:[1,0]
	v_pk_mul_f32 v[116:117], v[116:117], v[120:121]
	v_pk_mul_f32 v[88:89], v[88:89], v[148:149] op_sel_hi:[1,0]
	v_pk_mul_f32 v[112:113], v[112:113], v[116:117]
	v_mul_f32_e32 v116, 0xbfb8aa3b, v118
	v_mul_f32_e32 v117, 0xbfb8aa3b, v119
	v_exp_f32_e32 v116, v116
	v_exp_f32_e32 v117, v117
	v_cvt_pk_bf16_f32 v112, v112, v113
	v_pk_mul_f32 v[90:91], v[90:91], v[148:149] op_sel_hi:[1,0]
	v_add_f32_e32 v116, 1.0, v116
	v_add_f32_e32 v117, 1.0, v117
	v_rcp_f32_e32 v116, v116
	v_rcp_f32_e32 v117, v117
	v_pk_mul_f32 v[84:85], v[84:85], v[148:149] op_sel_hi:[1,0]
	v_pk_mul_f32 v[86:87], v[86:87], v[148:149] op_sel_hi:[1,0]
	v_pk_mul_f32 v[80:81], v[80:81], v[148:149] op_sel_hi:[1,0]
	v_pk_mul_f32 v[116:117], v[118:119], v[116:117]
	v_pk_mul_f32 v[82:83], v[82:83], v[148:149] op_sel_hi:[1,0]
	v_pk_mul_f32 v[114:115], v[114:115], v[116:117]
	v_pk_mul_f32 v[76:77], v[76:77], v[146:147] op_sel_hi:[1,0]
	v_cvt_pk_bf16_f32 v113, v114, v115
	v_mul_f32_e32 v114, 0xbfb8aa3b, v108
	v_mul_f32_e32 v115, 0xbfb8aa3b, v109
	v_exp_f32_e32 v114, v114
	v_exp_f32_e32 v115, v115
	v_mov_b32_e32 v252, v112
	v_mov_b32_e32 v253, v113
	v_lshl_add_u64 v[254:255], v[122:123], 0, v[248:249]
	s_nop 0
	v_permlane16_swap_b32_e32 v250, v252
	v_permlane16_swap_b32_e32 v251, v253
	global_store_dwordx4 v[254:255], v[250:253], off
	v_mad_i64_i32 v[112:113], s[12:13], v184, s18, v[128:129]
	v_add_f32_e32 v114, 1.0, v114
	v_add_f32_e32 v115, 1.0, v115
	v_rcp_f32_e32 v114, v114
; #define GAS __attribute__((address_space(1)))
; __device__ __forceinline__ unsigned pk2(float lo, float hi) { const f32x2 v = {lo, hi}; return __builtin_bit_cast(unsigned, __builtin_convertvector(v, hwbf16x2)); }
; __device__ __forceinline__ float silu_f(float x) { return x * fast_rcp(1.0f + __expf(-x)); }
; template <int MODE, bool SMALL>
; __device__ __forceinline__ float epi_apply(const EpiArgs& a, int row, int g32, int fq, f32x4 v0, f32x4 v1, float rstd) {
;     ...
;         v0 *= rstd; v1 *= rstd;
;         float h[4];
; #pragma unroll
;         for (int j = 0; j < 4; ++j) h[j] = silu_f(v0[j]) * v1[j];
;         u32x2 w; w.x = pk2(h[0], h[1]); w.y = pk2(h[2], h[3]);
;         *(GAS u32x2*)(a.out + (size_t)row * DFF + 16 * g32 + 4 * fq) = w;
;     __device__ __forceinline__ void operator()(const f32x4 (&acc)[2][2][4][2], const pg8::Unit& u, int wr, int wc, int fr, int fq) const {
;     ...
;                 for (int m = 0; m < 4; ++m) {
;                     const int row = u.pm * 256 + ai * 128 + wr * 64 + m * 16 + fr;
; #pragma unroll
;                     for (int bj = 0; bj < 2; ++bj) { const int g32 = (u.pn * 256 + bj * 128 + wc * 32) >> 5; (void)epi_apply<MODE, false>(a, row, g32, fq, acc[ai][bj][m][0], acc[ai][bj][m][1], rs[ai][m]); }
	v_rcp_f32_e32 v115, v115
	v_pk_mul_f32 v[78:79], v[78:79], v[146:147] op_sel_hi:[1,0]
	v_pk_mul_f32 v[72:73], v[72:73], v[146:147] op_sel_hi:[1,0]
	v_pk_mul_f32 v[74:75], v[74:75], v[146:147] op_sel_hi:[1,0]
	v_pk_mul_f32 v[108:109], v[108:109], v[114:115]
	v_pk_mul_f32 v[68:69], v[68:69], v[146:147] op_sel_hi:[1,0]
	v_pk_mul_f32 v[104:105], v[104:105], v[108:109]
	v_mul_f32_e32 v108, 0xbfb8aa3b, v110
	v_mul_f32_e32 v109, 0xbfb8aa3b, v111
	v_exp_f32_e32 v108, v108
	v_exp_f32_e32 v109, v109
	v_cvt_pk_bf16_f32 v104, v104, v105
	v_pk_mul_f32 v[70:71], v[70:71], v[146:147] op_sel_hi:[1,0]
	v_add_f32_e32 v108, 1.0, v108
	v_add_f32_e32 v109, 1.0, v109
	v_rcp_f32_e32 v108, v108
	v_rcp_f32_e32 v109, v109
	v_pk_mul_f32 v[64:65], v[64:65], v[146:147] op_sel_hi:[1,0]
	v_pk_mul_f32 v[66:67], v[66:67], v[146:147] op_sel_hi:[1,0]
	v_pk_mul_f32 v[60:61], v[60:61], v[140:141] op_sel_hi:[1,0]
	v_pk_mul_f32 v[108:109], v[110:111], v[108:109]
	v_pk_mul_f32 v[62:63], v[62:63], v[140:141] op_sel_hi:[1,0]
	v_pk_mul_f32 v[106:107], v[106:107], v[108:109]
	v_pk_mul_f32 v[56:57], v[56:57], v[140:141] op_sel_hi:[1,0]
	v_cvt_pk_bf16_f32 v105, v106, v107
	v_lshl_add_u64 v[106:107], v[112:113], 0, s[0:1]
	v_mov_b32_e32 v250, v104
	v_mov_b32_e32 v251, v105
	v_mul_f32_e32 v104, 0xbfb8aa3b, v100
	v_mul_f32_e32 v105, 0xbfb8aa3b, v101
	v_exp_f32_e32 v104, v104
	v_exp_f32_e32 v105, v105
	v_pk_mul_f32 v[58:59], v[58:59], v[140:141] op_sel_hi:[1,0]
	v_pk_mul_f32 v[52:53], v[52:53], v[140:141] op_sel_hi:[1,0]
	v_add_f32_e32 v104, 1.0, v104
	v_add_f32_e32 v105, 1.0, v105
	v_rcp_f32_e32 v104, v104
	v_rcp_f32_e32 v105, v105
	v_pk_mul_f32 v[54:55], v[54:55], v[140:141] op_sel_hi:[1,0]
	v_pk_mul_f32 v[48:49], v[48:49], v[140:141] op_sel_hi:[1,0]
	v_pk_mul_f32 v[50:51], v[50:51], v[140:141] op_sel_hi:[1,0]
	v_pk_mul_f32 v[100:101], v[100:101], v[104:105]
	v_pk_mul_f32 v[44:45], v[44:45], v[138:139] op_sel_hi:[1,0]
	v_pk_mul_f32 v[96:97], v[96:97], v[100:101]
	v_mul_f32_e32 v100, 0xbfb8aa3b, v102
	v_mul_f32_e32 v101, 0xbfb8aa3b, v103
	v_exp_f32_e32 v100, v100
	v_exp_f32_e32 v101, v101
	v_cvt_pk_bf16_f32 v96, v96, v97
	v_pk_mul_f32 v[46:47], v[46:47], v[138:139] op_sel_hi:[1,0]
	v_add_f32_e32 v100, 1.0, v100
	v_add_f32_e32 v101, 1.0, v101
	v_rcp_f32_e32 v100, v100
	v_rcp_f32_e32 v101, v101
	v_pk_mul_f32 v[40:41], v[40:41], v[138:139] op_sel_hi:[1,0]
	v_pk_mul_f32 v[42:43], v[42:43], v[138:139] op_sel_hi:[1,0]
	v_pk_mul_f32 v[36:37], v[36:37], v[138:139] op_sel_hi:[1,0]
	v_pk_mul_f32 v[100:101], v[102:103], v[100:101]
	v_pk_mul_f32 v[38:39], v[38:39], v[138:139] op_sel_hi:[1,0]
	v_pk_mul_f32 v[98:99], v[98:99], v[100:101]
	v_pk_mul_f32 v[32:33], v[32:33], v[138:139] op_sel_hi:[1,0]
	v_cvt_pk_bf16_f32 v97, v98, v99
	v_mul_f32_e32 v98, 0xbfb8aa3b, v92
	v_mul_f32_e32 v99, 0xbfb8aa3b, v93
	v_exp_f32_e32 v98, v98
	v_exp_f32_e32 v99, v99
	v_mov_b32_e32 v252, v96
	v_mov_b32_e32 v253, v97
	v_lshl_add_u64 v[254:255], v[106:107], 0, v[248:249]
	s_nop 0
	v_permlane16_swap_b32_e32 v250, v252
	v_permlane16_swap_b32_e32 v251, v253
	global_store_dwordx4 v[254:255], v[250:253], off
	v_mad_i64_i32 v[96:97], s[12:13], v182, s18, v[128:129]
	v_add_f32_e32 v98, 1.0, v98
	v_add_f32_e32 v99, 1.0, v99
	v_rcp_f32_e32 v98, v98
	v_rcp_f32_e32 v99, v99
	v_pk_mul_f32 v[34:35], v[34:35], v[138:139] op_sel_hi:[1,0]
	v_pk_mul_f32 v[28:29], v[28:29], v[132:133] op_sel_hi:[1,0]
	v_pk_mul_f32 v[30:31], v[30:31], v[132:133] op_sel_hi:[1,0]
	v_pk_mul_f32 v[92:93], v[92:93], v[98:99]
	v_pk_mul_f32 v[24:25], v[24:25], v[132:133] op_sel_hi:[1,0]
	v_pk_mul_f32 v[88:89], v[88:89], v[92:93]
	v_mul_f32_e32 v92, 0xbfb8aa3b, v94
	v_mul_f32_e32 v93, 0xbfb8aa3b, v95
	v_exp_f32_e32 v92, v92
	v_exp_f32_e32 v93, v93
	v_cvt_pk_bf16_f32 v88, v88, v89
	v_pk_mul_f32 v[26:27], v[26:27], v[132:133] op_sel_hi:[1,0]
	v_add_f32_e32 v92, 1.0, v92
	v_add_f32_e32 v93, 1.0, v93
	v_rcp_f32_e32 v92, v92
	v_rcp_f32_e32 v93, v93
	v_pk_mul_f32 v[20:21], v[20:21], v[132:133] op_sel_hi:[1,0]
	v_pk_mul_f32 v[22:23], v[22:23], v[132:133] op_sel_hi:[1,0]
	v_pk_mul_f32 v[16:17], v[16:17], v[132:133] op_sel_hi:[1,0]
	v_pk_mul_f32 v[92:93], v[94:95], v[92:93]
	v_pk_mul_f32 v[18:19], v[18:19], v[132:133] op_sel_hi:[1,0]
	v_pk_mul_f32 v[90:91], v[90:91], v[92:93]
	v_pk_mul_f32 v[12:13], v[12:13], v[130:131] op_sel_hi:[1,0]
	v_cvt_pk_bf16_f32 v89, v90, v91
	v_lshl_add_u64 v[90:91], v[96:97], 0, s[0:1]
	v_mov_b32_e32 v250, v88
	v_mov_b32_e32 v251, v89
	v_mul_f32_e32 v88, 0xbfb8aa3b, v84
	v_mul_f32_e32 v89, 0xbfb8aa3b, v85
	v_exp_f32_e32 v88, v88
	v_exp_f32_e32 v89, v89
	v_pk_mul_f32 v[14:15], v[14:15], v[130:131] op_sel_hi:[1,0]
	v_pk_mul_f32 v[8:9], v[8:9], v[130:131] op_sel_hi:[1,0]
	v_add_f32_e32 v88, 1.0, v88
	v_add_f32_e32 v89, 1.0, v89
	v_rcp_f32_e32 v88, v88
	v_rcp_f32_e32 v89, v89
	v_pk_mul_f32 v[10:11], v[10:11], v[130:131] op_sel_hi:[1,0]
	v_pk_mul_f32 v[4:5], v[4:5], v[130:131] op_sel_hi:[1,0]
	v_pk_mul_f32 v[6:7], v[6:7], v[130:131] op_sel_hi:[1,0]
	v_pk_mul_f32 v[84:85], v[84:85], v[88:89]
	v_pk_mul_f32 v[0:1], v[0:1], v[130:131] op_sel_hi:[1,0]
	v_pk_mul_f32 v[80:81], v[80:81], v[84:85]
	v_mul_f32_e32 v84, 0xbfb8aa3b, v86
	v_mul_f32_e32 v85, 0xbfb8aa3b, v87
	v_exp_f32_e32 v84, v84
	v_exp_f32_e32 v85, v85
	v_cvt_pk_bf16_f32 v80, v80, v81
	v_pk_mul_f32 v[2:3], v[2:3], v[130:131] op_sel_hi:[1,0]
	v_add_f32_e32 v84, 1.0, v84
	v_add_f32_e32 v85, 1.0, v85
	v_rcp_f32_e32 v84, v84
	v_rcp_f32_e32 v85, v85
	s_and_b64 vcc, exec, s[38:39]
	v_pk_mul_f32 v[84:85], v[86:87], v[84:85]
	s_nop 0
	v_pk_mul_f32 v[82:83], v[82:83], v[84:85]
	s_nop 0
	v_cvt_pk_bf16_f32 v81, v82, v83
	v_mul_f32_e32 v82, 0xbfb8aa3b, v76
	v_mul_f32_e32 v83, 0xbfb8aa3b, v77
; #define GAS __attribute__((address_space(1)))
; __device__ __forceinline__ unsigned pk2(float lo, float hi) { const f32x2 v = {lo, hi}; return __builtin_bit_cast(unsigned, __builtin_convertvector(v, hwbf16x2)); }
; __device__ __forceinline__ float silu_f(float x) { return x * fast_rcp(1.0f + __expf(-x)); }
; template <int MODE, bool SMALL>
; __device__ __forceinline__ float epi_apply(const EpiArgs& a, int row, int g32, int fq, f32x4 v0, f32x4 v1, float rstd) {
;     ...
;         v0 *= rstd; v1 *= rstd;
;         float h[4];
; #pragma unroll
;         for (int j = 0; j < 4; ++j) h[j] = silu_f(v0[j]) * v1[j];
;         u32x2 w; w.x = pk2(h[0], h[1]); w.y = pk2(h[2], h[3]);
;         *(GAS u32x2*)(a.out + (size_t)row * DFF + 16 * g32 + 4 * fq) = w;
;     __device__ __forceinline__ void operator()(const f32x4 (&acc)[2][2][4][2], const pg8::Unit& u, int wr, int wc, int fr, int fq) const {
;     ...
;                 for (int m = 0; m < 4; ++m) {
;                     const int row = u.pm * 256 + ai * 128 + wr * 64 + m * 16 + fr;
; #pragma unroll
;                     for (int bj = 0; bj < 2; ++bj) { const int g32 = (u.pn * 256 + bj * 128 + wc * 32) >> 5; (void)epi_apply<MODE, false>(a, row, g32, fq, acc[ai][bj][m][0], acc[ai][bj][m][1], rs[ai][m]); }
	v_exp_f32_e32 v82, v82
	v_exp_f32_e32 v83, v83
	v_mov_b32_e32 v252, v80
	v_mov_b32_e32 v253, v81
	v_lshl_add_u64 v[254:255], v[90:91], 0, v[248:249]
	s_nop 0
	v_permlane16_swap_b32_e32 v250, v252
	v_permlane16_swap_b32_e32 v251, v253
	global_store_dwordx4 v[254:255], v[250:253], off
	v_mad_i64_i32 v[80:81], s[12:13], v180, s18, v[128:129]
	v_add_f32_e32 v82, 1.0, v82
	v_add_f32_e32 v83, 1.0, v83
	v_rcp_f32_e32 v82, v82
	v_rcp_f32_e32 v83, v83
	s_nop 0
	v_pk_mul_f32 v[76:77], v[76:77], v[82:83]
	s_nop 0
	v_pk_mul_f32 v[72:73], v[72:73], v[76:77]
	v_mul_f32_e32 v76, 0xbfb8aa3b, v78
	v_mul_f32_e32 v77, 0xbfb8aa3b, v79
	v_exp_f32_e32 v76, v76
	v_exp_f32_e32 v77, v77
	v_cvt_pk_bf16_f32 v72, v72, v73
	v_add_f32_e32 v76, 1.0, v76
	v_add_f32_e32 v77, 1.0, v77
	v_rcp_f32_e32 v76, v76
	v_rcp_f32_e32 v77, v77
	s_nop 0
	v_pk_mul_f32 v[76:77], v[78:79], v[76:77]
	s_nop 0
	v_pk_mul_f32 v[74:75], v[74:75], v[76:77]
	s_nop 0
	v_cvt_pk_bf16_f32 v73, v74, v75
	v_lshl_add_u64 v[74:75], v[80:81], 0, s[0:1]
	v_mov_b32_e32 v250, v72
	v_mov_b32_e32 v251, v73
	v_mul_f32_e32 v72, 0xbfb8aa3b, v68
	v_mul_f32_e32 v73, 0xbfb8aa3b, v69
	v_exp_f32_e32 v72, v72
	v_exp_f32_e32 v73, v73
	v_add_f32_e32 v72, 1.0, v72
	v_add_f32_e32 v73, 1.0, v73
	v_rcp_f32_e32 v72, v72
	v_rcp_f32_e32 v73, v73
	s_nop 0
	v_pk_mul_f32 v[68:69], v[68:69], v[72:73]
	s_nop 0
	v_pk_mul_f32 v[64:65], v[64:65], v[68:69]
	v_mul_f32_e32 v68, 0xbfb8aa3b, v70
	v_mul_f32_e32 v69, 0xbfb8aa3b, v71
	v_exp_f32_e32 v68, v68
	v_exp_f32_e32 v69, v69
	v_cvt_pk_bf16_f32 v64, v64, v65
	v_add_f32_e32 v68, 1.0, v68
	v_add_f32_e32 v69, 1.0, v69
	v_rcp_f32_e32 v68, v68
	v_rcp_f32_e32 v69, v69
	s_nop 0
	v_pk_mul_f32 v[68:69], v[70:71], v[68:69]
	s_nop 0
	v_pk_mul_f32 v[66:67], v[66:67], v[68:69]
	s_nop 0
	v_cvt_pk_bf16_f32 v65, v66, v67
	v_mul_f32_e32 v66, 0xbfb8aa3b, v60
	v_mul_f32_e32 v67, 0xbfb8aa3b, v61
	v_exp_f32_e32 v66, v66
	v_exp_f32_e32 v67, v67
	v_mov_b32_e32 v252, v64
	v_mov_b32_e32 v253, v65
	v_lshl_add_u64 v[254:255], v[74:75], 0, v[248:249]
	s_nop 0
	v_permlane16_swap_b32_e32 v250, v252
	v_permlane16_swap_b32_e32 v251, v253
	global_store_dwordx4 v[254:255], v[250:253], off
	v_mad_i64_i32 v[64:65], s[12:13], v178, s18, v[128:129]
	v_add_f32_e32 v66, 1.0, v66
	v_add_f32_e32 v67, 1.0, v67
	v_rcp_f32_e32 v66, v66
	v_rcp_f32_e32 v67, v67
	s_nop 0
	v_pk_mul_f32 v[60:61], v[60:61], v[66:67]
	s_nop 0
	v_pk_mul_f32 v[56:57], v[56:57], v[60:61]
	v_mul_f32_e32 v60, 0xbfb8aa3b, v62
	v_mul_f32_e32 v61, 0xbfb8aa3b, v63
	v_exp_f32_e32 v60, v60
	v_exp_f32_e32 v61, v61
	v_cvt_pk_bf16_f32 v56, v56, v57
	v_add_f32_e32 v60, 1.0, v60
	v_add_f32_e32 v61, 1.0, v61
	v_rcp_f32_e32 v60, v60
	v_rcp_f32_e32 v61, v61
	s_nop 0
	v_pk_mul_f32 v[60:61], v[62:63], v[60:61]
	s_nop 0
	v_pk_mul_f32 v[58:59], v[58:59], v[60:61]
	s_nop 0
	v_cvt_pk_bf16_f32 v57, v58, v59
	v_lshl_add_u64 v[58:59], v[64:65], 0, s[0:1]
	v_mov_b32_e32 v250, v56
	v_mov_b32_e32 v251, v57
	v_mul_f32_e32 v56, 0xbfb8aa3b, v52
	v_mul_f32_e32 v57, 0xbfb8aa3b, v53
	v_exp_f32_e32 v56, v56
	v_exp_f32_e32 v57, v57
	v_add_f32_e32 v56, 1.0, v56
	v_add_f32_e32 v57, 1.0, v57
	v_rcp_f32_e32 v56, v56
	v_rcp_f32_e32 v57, v57
	s_nop 0
	v_pk_mul_f32 v[52:53], v[52:53], v[56:57]
	s_nop 0
	v_pk_mul_f32 v[48:49], v[48:49], v[52:53]
	v_mul_f32_e32 v52, 0xbfb8aa3b, v54
	v_mul_f32_e32 v53, 0xbfb8aa3b, v55
	v_exp_f32_e32 v52, v52
	v_exp_f32_e32 v53, v53
	v_cvt_pk_bf16_f32 v48, v48, v49
	v_add_f32_e32 v52, 1.0, v52
	v_add_f32_e32 v53, 1.0, v53
	v_rcp_f32_e32 v52, v52
	v_rcp_f32_e32 v53, v53
	s_nop 0
	v_pk_mul_f32 v[52:53], v[54:55], v[52:53]
	s_nop 0
	v_pk_mul_f32 v[50:51], v[50:51], v[52:53]
	s_nop 0
	v_cvt_pk_bf16_f32 v49, v50, v51
	v_mul_f32_e32 v50, 0xbfb8aa3b, v44
	v_mul_f32_e32 v51, 0xbfb8aa3b, v45
	v_exp_f32_e32 v50, v50
	v_exp_f32_e32 v51, v51
	v_mov_b32_e32 v252, v48
	v_mov_b32_e32 v253, v49
	v_lshl_add_u64 v[254:255], v[58:59], 0, v[248:249]
	s_nop 0
	v_permlane16_swap_b32_e32 v250, v252
	v_permlane16_swap_b32_e32 v251, v253
	global_store_dwordx4 v[254:255], v[250:253], off
	v_mad_i64_i32 v[48:49], s[12:13], v176, s18, v[128:129]
	v_add_f32_e32 v50, 1.0, v50
	v_add_f32_e32 v51, 1.0, v51
	v_rcp_f32_e32 v50, v50
	v_rcp_f32_e32 v51, v51
	s_nop 0
	v_pk_mul_f32 v[44:45], v[44:45], v[50:51]
	s_nop 0
	v_pk_mul_f32 v[40:41], v[40:41], v[44:45]
	v_mul_f32_e32 v44, 0xbfb8aa3b, v46
	v_mul_f32_e32 v45, 0xbfb8aa3b, v47
	v_exp_f32_e32 v44, v44
	v_exp_f32_e32 v45, v45
	v_cvt_pk_bf16_f32 v40, v40, v41
	v_add_f32_e32 v44, 1.0, v44
	v_add_f32_e32 v45, 1.0, v45
	v_rcp_f32_e32 v44, v44
	v_rcp_f32_e32 v45, v45
	s_nop 0
	v_pk_mul_f32 v[44:45], v[46:47], v[44:45]
	s_nop 0
	v_pk_mul_f32 v[42:43], v[42:43], v[44:45]
	s_nop 0
	v_cvt_pk_bf16_f32 v41, v42, v43
	v_lshl_add_u64 v[42:43], v[48:49], 0, s[0:1]
	v_mov_b32_e32 v250, v40
	v_mov_b32_e32 v251, v41
; #define GAS __attribute__((address_space(1)))
; __device__ __forceinline__ unsigned pk2(float lo, float hi) { const f32x2 v = {lo, hi}; return __builtin_bit_cast(unsigned, __builtin_convertvector(v, hwbf16x2)); }
; __device__ __forceinline__ float silu_f(float x) { return x * fast_rcp(1.0f + __expf(-x)); }
; template <int MODE, bool SMALL>
; __device__ __forceinline__ float epi_apply(const EpiArgs& a, int row, int g32, int fq, f32x4 v0, f32x4 v1, float rstd) {
;     ...
;         v0 *= rstd; v1 *= rstd;
;         float h[4];
; #pragma unroll
;         for (int j = 0; j < 4; ++j) h[j] = silu_f(v0[j]) * v1[j];
;         u32x2 w; w.x = pk2(h[0], h[1]); w.y = pk2(h[2], h[3]);
;         *(GAS u32x2*)(a.out + (size_t)row * DFF + 16 * g32 + 4 * fq) = w;
;     __device__ __forceinline__ void operator()(const f32x4 (&acc)[2][2][4][2], const pg8::Unit& u, int wr, int wc, int fr, int fq) const {
;     ...
;                 for (int m = 0; m < 4; ++m) {
;                     const int row = u.pm * 256 + ai * 128 + wr * 64 + m * 16 + fr;
; #pragma unroll
;                     for (int bj = 0; bj < 2; ++bj) { const int g32 = (u.pn * 256 + bj * 128 + wc * 32) >> 5; (void)epi_apply<MODE, false>(a, row, g32, fq, acc[ai][bj][m][0], acc[ai][bj][m][1], rs[ai][m]); }
	v_mul_f32_e32 v40, 0xbfb8aa3b, v36
	v_mul_f32_e32 v41, 0xbfb8aa3b, v37
	v_exp_f32_e32 v40, v40
	v_exp_f32_e32 v41, v41
	v_add_f32_e32 v40, 1.0, v40
	v_add_f32_e32 v41, 1.0, v41
	v_rcp_f32_e32 v40, v40
	v_rcp_f32_e32 v41, v41
	s_nop 0
	v_pk_mul_f32 v[36:37], v[36:37], v[40:41]
	s_nop 0
	v_pk_mul_f32 v[32:33], v[32:33], v[36:37]
	v_mul_f32_e32 v36, 0xbfb8aa3b, v38
	v_mul_f32_e32 v37, 0xbfb8aa3b, v39
	v_exp_f32_e32 v36, v36
	v_exp_f32_e32 v37, v37
	v_cvt_pk_bf16_f32 v32, v32, v33
	v_add_f32_e32 v36, 1.0, v36
	v_add_f32_e32 v37, 1.0, v37
	v_rcp_f32_e32 v36, v36
	v_rcp_f32_e32 v37, v37
	s_nop 0
	v_pk_mul_f32 v[36:37], v[38:39], v[36:37]
	s_nop 0
	v_pk_mul_f32 v[34:35], v[34:35], v[36:37]
	s_nop 0
	v_cvt_pk_bf16_f32 v33, v34, v35
	v_mul_f32_e32 v34, 0xbfb8aa3b, v28
	v_mul_f32_e32 v35, 0xbfb8aa3b, v29
	v_exp_f32_e32 v34, v34
	v_exp_f32_e32 v35, v35
	v_mov_b32_e32 v252, v32
	v_mov_b32_e32 v253, v33
	v_lshl_add_u64 v[254:255], v[42:43], 0, v[248:249]
	s_nop 0
	v_permlane16_swap_b32_e32 v250, v252
	v_permlane16_swap_b32_e32 v251, v253
	global_store_dwordx4 v[254:255], v[250:253], off
	v_mad_i64_i32 v[32:33], s[12:13], v174, s18, v[128:129]
	v_add_f32_e32 v34, 1.0, v34
	v_add_f32_e32 v35, 1.0, v35
	v_rcp_f32_e32 v34, v34
	v_rcp_f32_e32 v35, v35
	s_nop 0
	v_pk_mul_f32 v[28:29], v[28:29], v[34:35]
	s_nop 0
	v_pk_mul_f32 v[24:25], v[24:25], v[28:29]
	v_mul_f32_e32 v28, 0xbfb8aa3b, v30
	v_mul_f32_e32 v29, 0xbfb8aa3b, v31
	v_exp_f32_e32 v28, v28
	v_exp_f32_e32 v29, v29
	v_cvt_pk_bf16_f32 v24, v24, v25
	v_add_f32_e32 v28, 1.0, v28
	v_add_f32_e32 v29, 1.0, v29
	v_rcp_f32_e32 v28, v28
	v_rcp_f32_e32 v29, v29
	s_nop 0
	v_pk_mul_f32 v[28:29], v[30:31], v[28:29]
	s_nop 0
	v_pk_mul_f32 v[26:27], v[26:27], v[28:29]
	s_nop 0
	v_cvt_pk_bf16_f32 v25, v26, v27
	v_lshl_add_u64 v[26:27], v[32:33], 0, s[0:1]
	v_mov_b32_e32 v250, v24
	v_mov_b32_e32 v251, v25
	v_mul_f32_e32 v24, 0xbfb8aa3b, v20
	v_mul_f32_e32 v25, 0xbfb8aa3b, v21
	v_exp_f32_e32 v24, v24
	v_exp_f32_e32 v25, v25
	v_add_f32_e32 v24, 1.0, v24
	v_add_f32_e32 v25, 1.0, v25
	v_rcp_f32_e32 v24, v24
	v_rcp_f32_e32 v25, v25
	s_nop 0
	v_pk_mul_f32 v[20:21], v[20:21], v[24:25]
	s_nop 0
	v_pk_mul_f32 v[16:17], v[16:17], v[20:21]
	v_mul_f32_e32 v20, 0xbfb8aa3b, v22
	v_mul_f32_e32 v21, 0xbfb8aa3b, v23
	v_exp_f32_e32 v20, v20
	v_exp_f32_e32 v21, v21
	v_cvt_pk_bf16_f32 v16, v16, v17
	v_add_f32_e32 v20, 1.0, v20
	v_add_f32_e32 v21, 1.0, v21
	v_rcp_f32_e32 v20, v20
	v_rcp_f32_e32 v21, v21
	s_nop 0
	v_pk_mul_f32 v[20:21], v[22:23], v[20:21]
	s_nop 0
	v_pk_mul_f32 v[18:19], v[18:19], v[20:21]
	s_nop 0
	v_cvt_pk_bf16_f32 v17, v18, v19
	v_mul_f32_e32 v18, 0xbfb8aa3b, v12
	v_mul_f32_e32 v19, 0xbfb8aa3b, v13
	v_exp_f32_e32 v18, v18
	v_exp_f32_e32 v19, v19
	v_mov_b32_e32 v252, v16
	v_mov_b32_e32 v253, v17
	v_lshl_add_u64 v[254:255], v[26:27], 0, v[248:249]
	s_nop 0
	v_permlane16_swap_b32_e32 v250, v252
	v_permlane16_swap_b32_e32 v251, v253
	global_store_dwordx4 v[254:255], v[250:253], off
	v_mad_i64_i32 v[16:17], s[12:13], v172, s18, v[128:129]
	v_add_f32_e32 v18, 1.0, v18
	v_add_f32_e32 v19, 1.0, v19
	v_rcp_f32_e32 v18, v18
	v_rcp_f32_e32 v19, v19
	s_nop 0
	v_pk_mul_f32 v[12:13], v[12:13], v[18:19]
	s_nop 0
	v_pk_mul_f32 v[8:9], v[8:9], v[12:13]
	v_mul_f32_e32 v12, 0xbfb8aa3b, v14
	v_mul_f32_e32 v13, 0xbfb8aa3b, v15
	v_exp_f32_e32 v12, v12
	v_exp_f32_e32 v13, v13
	v_cvt_pk_bf16_f32 v8, v8, v9
	v_add_f32_e32 v12, 1.0, v12
	v_add_f32_e32 v13, 1.0, v13
	v_rcp_f32_e32 v12, v12
	v_rcp_f32_e32 v13, v13
	s_nop 0
	v_pk_mul_f32 v[12:13], v[14:15], v[12:13]
	s_nop 0
	v_pk_mul_f32 v[10:11], v[10:11], v[12:13]
	s_nop 0
	v_cvt_pk_bf16_f32 v9, v10, v11
	v_lshl_add_u64 v[10:11], v[16:17], 0, s[0:1]
	v_mov_b32_e32 v250, v8
	v_mov_b32_e32 v251, v9
	v_mul_f32_e32 v8, 0xbfb8aa3b, v4
	v_mul_f32_e32 v9, 0xbfb8aa3b, v5
	v_exp_f32_e32 v8, v8
	v_exp_f32_e32 v9, v9
	s_mov_b64 s[0:1], -1
	v_add_f32_e32 v8, 1.0, v8
	v_add_f32_e32 v9, 1.0, v9
	v_rcp_f32_e32 v8, v8
	v_rcp_f32_e32 v9, v9
	s_nop 0
	v_pk_mul_f32 v[4:5], v[4:5], v[8:9]
	s_nop 0
	v_pk_mul_f32 v[0:1], v[0:1], v[4:5]
	v_mul_f32_e32 v4, 0xbfb8aa3b, v6
	v_mul_f32_e32 v5, 0xbfb8aa3b, v7
	v_exp_f32_e32 v4, v4
	v_exp_f32_e32 v5, v5
	v_cvt_pk_bf16_f32 v0, v0, v1
	v_add_f32_e32 v4, 1.0, v4
	v_add_f32_e32 v5, 1.0, v5
	v_rcp_f32_e32 v4, v4
	v_rcp_f32_e32 v5, v5
	s_nop 0
	v_pk_mul_f32 v[4:5], v[6:7], v[4:5]
	s_nop 0
	v_pk_mul_f32 v[2:3], v[2:3], v[4:5]
	s_nop 0
	v_cvt_pk_bf16_f32 v1, v2, v3
	v_mov_b32_e32 v252, v0
	v_mov_b32_e32 v253, v1
	v_lshl_add_u64 v[254:255], v[10:11], 0, v[248:249]
	s_nop 0
	v_permlane16_swap_b32_e32 v250, v252
	v_permlane16_swap_b32_e32 v251, v253
	global_store_dwordx4 v[254:255], v[250:253], off
	s_cbranch_vccnz .LBB0_303
	s_andn2_b64 vcc, exec, s[64:65]
	s_cbranch_vccnz .LBB0_302
	s_barrier
	s_branch .LBB0_302

; __global__ void __launch_bounds__(512, 2) hybrid_fwd(Params P) {
	.amdhsa_kernel _Z10hybrid_fwd6Params
		.amdhsa_group_segment_fixed_size 0
		.amdhsa_private_segment_fixed_size 0
		.amdhsa_kernarg_size 480
		.amdhsa_user_sgpr_count 2
		.amdhsa_user_sgpr_dispatch_ptr 0
		.amdhsa_user_sgpr_queue_ptr 0
		.amdhsa_user_sgpr_kernarg_segment_ptr 1
		.amdhsa_user_sgpr_dispatch_id 0
		.amdhsa_user_sgpr_kernarg_preload_length 0
		.amdhsa_user_sgpr_kernarg_preload_offset 0
		.amdhsa_user_sgpr_private_segment_size 0
		.amdhsa_uses_dynamic_stack 0
		.amdhsa_enable_private_segment 0
		.amdhsa_system_sgpr_workgroup_id_x 1
		.amdhsa_system_sgpr_workgroup_id_y 0
		.amdhsa_system_sgpr_workgroup_id_z 0
		.amdhsa_system_sgpr_workgroup_info 0
		.amdhsa_system_vgpr_workitem_id 2
		.amdhsa_next_free_vgpr 256
		.amdhsa_next_free_sgpr 98
		.amdhsa_accum_offset 256
		.amdhsa_reserve_vcc 1
		.amdhsa_float_round_mode_32 0
		.amdhsa_float_round_mode_16_64 0
		.amdhsa_float_denorm_mode_32 3
		.amdhsa_float_denorm_mode_16_64 3
		.amdhsa_dx10_clamp 1
		.amdhsa_ieee_mode 1
		.amdhsa_fp16_overflow 0
		.amdhsa_tg_split 0
		.amdhsa_exception_fp_ieee_invalid_op 0
		.amdhsa_exception_fp_denorm_src 0
		.amdhsa_exception_fp_ieee_div_zero 0
		.amdhsa_exception_fp_ieee_overflow 0
		.amdhsa_exception_fp_ieee_underflow 0
		.amdhsa_exception_fp_ieee_inexact 0
		.amdhsa_exception_int_div_zero 0
	.end_amdhsa_kernel

; __global__ void __launch_bounds__(512, 2) hybrid_fwd(Params P) {
amdhsa.kernels:
  - .agpr_count:     0
    .args:
      - .offset:         0
        .size:           224
        .value_kind:     by_value
      - .offset:         224
        .size:           4
        .value_kind:     hidden_block_count_x
      - .offset:         228
        .size:           4
        .value_kind:     hidden_block_count_y
      - .offset:         232
        .size:           4
        .value_kind:     hidden_block_count_z
      - .offset:         236
        .size:           2
        .value_kind:     hidden_group_size_x
      - .offset:         238
        .size:           2
        .value_kind:     hidden_group_size_y
      - .offset:         240
        .size:           2
        .value_kind:     hidden_group_size_z
      - .offset:         242
        .size:           2
        .value_kind:     hidden_remainder_x
      - .offset:         244
        .size:           2
        .value_kind:     hidden_remainder_y
      - .offset:         246
        .size:           2
        .value_kind:     hidden_remainder_z
      - .offset:         264
        .size:           8
        .value_kind:     hidden_global_offset_x
      - .offset:         272
        .size:           8
        .value_kind:     hidden_global_offset_y
      - .offset:         280
        .size:           8
        .value_kind:     hidden_global_offset_z
      - .offset:         288
        .size:           2
        .value_kind:     hidden_grid_dims
      - .offset:         312
        .size:           8
        .value_kind:     hidden_multigrid_sync_arg
      - .offset:         344
        .size:           4
        .value_kind:     hidden_dynamic_lds_size
    .group_segment_fixed_size: 0
    .kernarg_segment_align: 8
    .kernarg_segment_size: 480
    .language:       OpenCL C
    .language_version:
      - 2
      - 0
    .max_flat_workgroup_size: 512
    .name:           _Z10hybrid_fwd6Params
    .private_segment_fixed_size: 0
    .sgpr_count:     104
    .sgpr_spill_count: 197
    .symbol:         _Z10hybrid_fwd6Params.kd
    .uniform_work_group_size: 1
    .uses_dynamic_stack: false
    .vgpr_count:     256
    .vgpr_spill_count: 0
    .wavefront_size: 64
